# normmod2: lane-pair exchange so H rows are stored as 16-byte write-through stores (nothing dirty left for the barrier's L2 write-back)
# baseline (speedup 1.0000x reference)
.LBB0_201:
	s_and_b64 vcc, exec, s[2:3]
	v_readlane_b32 s16, v254, 8
	v_readlane_b32 s17, v254, 9
	s_cbranch_vccz .LBB0_211
	v_readlane_b32 s46, v252, 11
	s_cmp_gt_i32 s92, 4
	s_mov_b64 s[2:3], -1
	v_readlane_b32 s47, v252, 12
	s_cbranch_scc0 .LBB0_207
	v_readlane_b32 s0, v253, 0
	v_mov_b32_e32 v2, v1
	s_nop 0
	v_ashrrev_i32_e32 v2, 5, v2
	v_and_b32_e32 v2, -2, v2
	v_lshl_add_u32 v10, s0, 4, v2
	s_movk_i32 s0, 0x2000
	v_cmp_gt_i32_e32 vcc, s0, v10
	s_and_saveexec_b64 s[2:3], vcc
	v_readlane_b32 s24, v254, 22
	v_readlane_b32 s68, v254, 60
	s_movk_i32 s17, 0xfff
	v_readlane_b32 s25, v254, 23
	s_mov_b32 s30, 0x3a800000
	s_mov_b64 s[36:37], 0x4000
	v_readlane_b32 s72, v252, 0
	v_readlane_b32 s73, v252, 1
	v_readlane_b32 s74, v252, 2
	v_readlane_b32 s75, v252, 3
	v_readlane_b32 s69, v254, 61
	v_readlane_b32 s70, v254, 62
	v_readlane_b32 s71, v254, 63
	s_cbranch_execz .LBB0_206
	s_lshl_b32 s0, s82, 10
	s_mov_b64 s[40:41], s[72:73]
	s_ashr_i32 s1, s0, 31
	s_mov_b64 s[42:43], s[74:75]
	s_lshl_b64 s[0:1], s[0:1], 2
	v_readlane_b32 s68, v254, 36
	v_readlane_b32 s69, v254, 37
	v_readlane_b32 s70, v254, 38
	v_readlane_b32 s71, v254, 39
	v_readlane_b32 s72, v254, 40
	v_readlane_b32 s73, v254, 41
	v_readlane_b32 s74, v254, 42
	v_readlane_b32 s75, v254, 43
	s_waitcnt lgkmcnt(0)
	s_add_u32 s6, s68, s0
	s_addc_u32 s7, s69, s1
	v_readlane_b32 s68, v254, 44
	v_ashrrev_i32_e32 v11, 31, v10
	v_readlane_b32 s82, v254, 58
	v_readlane_b32 s83, v254, 59
	v_lshlrev_b64 v[12:13], 11, v[10:11]
	s_mov_b64 s[12:13], 0
	s_mov_b64 s[14:15], s[42:43]
	s_mov_b64 s[18:19], s[82:83]
	v_readlane_b32 s82, v252, 8
	v_readlane_b32 s69, v254, 45
	v_readlane_b32 s70, v254, 46
	v_readlane_b32 s71, v254, 47
	v_readlane_b32 s72, v254, 48
	v_readlane_b32 s73, v254, 49
	v_readlane_b32 s74, v254, 50
	v_readlane_b32 s75, v254, 51
	v_readlane_b32 s76, v254, 52
	v_readlane_b32 s77, v254, 53
	v_readlane_b32 s78, v254, 54
	v_readlane_b32 s79, v254, 55
	v_readlane_b32 s80, v254, 56
	v_readlane_b32 s81, v254, 57
	v_readlane_b32 s83, v252, 9
	s_mov_b32 s78, 0x55555555
	s_mov_b32 s79, 0x55555555
	v_and_b32_e32 v110, 1, v194
	v_mul_u32_u24_e32 v110, 0x7f8, v110
	v_mov_b32_e32 v111, 0
.LBB0_205:
	v_mov_b32_e32 v4, v1
	v_cmp_lt_i32_e32 vcc, v196, v195
	v_and_b32_e32 v2, 63, v4
	v_lshlrev_b32_e32 v162, 3, v2
	v_lshl_add_u64 v[2:3], s[14:15], 0, v[12:13]
	v_lshl_add_u64 v[2:3], v[2:3], 0, v[162:163]
	global_load_dwordx2 v[20:21], v[2:3], off sc1
	global_load_dwordx2 v[40:41], v[2:3], off offset:512 sc1
	global_load_dwordx2 v[24:25], v[2:3], off offset:1024 sc1
	global_load_dwordx2 v[42:43], v[2:3], off offset:1536 sc1
	global_load_dwordx2 v[30:31], v[2:3], off offset:2048 sc1
	global_load_dwordx2 v[38:39], v[2:3], off offset:2560 sc1
	global_load_dwordx2 v[22:23], v[2:3], off offset:3072 sc1
	global_load_dwordx2 v[46:47], v[2:3], off offset:3584 sc1
	v_cndmask_b32_e32 v2, v194, v196, vcc
	v_cmp_lt_i32_e32 vcc, v197, v195
	v_lshlrev_b32_e32 v11, 2, v2
	s_mul_i32 s0, s82, 5
	v_cndmask_b32_e32 v2, v194, v197, vcc
	v_cmp_lt_i32_e32 vcc, v198, v195
	s_waitcnt vmcnt(20)
	v_lshlrev_b32_e32 v74, 2, v2
	v_mov_b32_e32 v15, v163
	v_cndmask_b32_e32 v2, v194, v198, vcc
	v_cmp_lt_i32_e32 vcc, v199, v195
	v_lshlrev_b32_e32 v75, 2, v2
	s_waitcnt vmcnt(7)
	v_and_b32_e32 v33, 0xffff0000, v20
	v_cndmask_b32_e32 v2, v194, v199, vcc
	v_cmp_lt_i32_e32 vcc, v200, v195
	v_lshlrev_b32_e32 v76, 2, v2
	s_waitcnt vmcnt(6)
	v_and_b32_e32 v59, 0xffff0000, v40
	v_cndmask_b32_e32 v2, v194, v200, vcc
	v_cmp_lt_i32_e32 vcc, v201, v195
	v_lshlrev_b32_e32 v77, 2, v2
	v_lshlrev_b32_e32 v32, 16, v20
	v_cndmask_b32_e32 v2, v194, v201, vcc
	v_lshlrev_b32_e32 v78, 2, v2
	v_add_u32_e32 v2, 0xfffff000, v10
	v_lshrrev_b32_e32 v2, 10, v2
	v_add_u32_e32 v2, 1, v2
	v_cmp_lt_i32_e32 vcc, s17, v10
	v_lshlrev_b32_e32 v58, 16, v40
	v_mov_b32_e32 v52, v33
	v_cndmask_b32_e32 v2, 0, v2, vcc
	v_add_u32_e32 v5, s0, v2
	v_mov_b64_e32 v[2:3], s[40:41]
	v_mad_i64_i32 v[2:3], s[0:1], v5, s29, v[2:3]
	s_mov_b64 s[0:1], 0x3000
	s_nop 0
	v_lshl_add_u64 v[44:45], v[2:3], 0, s[0:1]
	v_lshl_add_u64 v[60:61], v[2:3], 0, s[36:37]
	v_lshlrev_b32_e32 v2, 4, v4
	v_and_b32_e32 v14, 0x3f0, v2
	v_lshl_add_u64 v[2:3], v[44:45], 0, v[14:15]
	v_lshl_add_u64 v[16:17], v[60:61], 0, v[14:15]
	global_load_dwordx4 v[2:5], v[2:3], off
	v_mov_b32_e32 v53, v59
	global_load_dwordx4 v[16:19], v[16:17], off
	v_lshlrev_b32_e32 v28, 16, v21
	global_load_dwordx4 v[6:9], v14, s[6:7]
	v_lshlrev_b32_e32 v56, 16, v41
	v_mov_b32_e32 v50, v32
	v_mov_b32_e32 v51, v58
	v_pk_mul_f32 v[52:53], v[52:53], v[52:53]
	v_and_b32_e32 v57, 0xffff0000, v41
	v_mov_b32_e32 v40, v28
	v_mov_b32_e32 v41, v56
	v_pk_fma_f32 v[50:51], v[50:51], v[50:51], v[52:53]
	v_and_b32_e32 v29, 0xffff0000, v21
	s_waitcnt vmcnt(6)
	v_and_b32_e32 v35, 0xffff0000, v30
	v_pk_fma_f32 v[40:41], v[40:41], v[40:41], v[50:51]
	s_waitcnt vmcnt(5)
	v_and_b32_e32 v51, 0xffff0000, v38
	v_lshlrev_b32_e32 v34, 16, v30
	v_mov_b32_e32 v48, v29
	v_mov_b32_e32 v49, v57
	v_lshlrev_b32_e32 v50, 16, v38
	v_mov_b32_e32 v54, v35
	v_mov_b32_e32 v55, v51
	v_lshlrev_b32_e32 v26, 16, v31
	v_pk_fma_f32 v[62:63], v[48:49], v[48:49], v[40:41]
	v_lshlrev_b32_e32 v48, 16, v39
	v_mov_b32_e32 v52, v34
	v_mov_b32_e32 v53, v50
	v_pk_mul_f32 v[54:55], v[54:55], v[54:55]
	v_and_b32_e32 v27, 0xffff0000, v31
	v_and_b32_e32 v49, 0xffff0000, v39
	v_mov_b32_e32 v38, v26
	v_mov_b32_e32 v39, v48
	v_pk_fma_f32 v[52:53], v[52:53], v[52:53], v[54:55]
	v_mov_b32_e32 v40, v27
	v_mov_b32_e32 v41, v49
	v_pk_fma_f32 v[38:39], v[38:39], v[38:39], v[52:53]
	v_and_b32_e32 v67, 0xffff0000, v24
	v_and_b32_e32 v71, 0xffff0000, v42
	v_pk_fma_f32 v[68:69], v[40:41], v[40:41], v[38:39]
	v_lshlrev_b32_e32 v66, 16, v24
	v_lshlrev_b32_e32 v70, 16, v42
	v_mov_b32_e32 v80, v67
	v_mov_b32_e32 v81, v71
	v_lshlrev_b32_e32 v64, 16, v25
	s_waitcnt vmcnt(4)
	v_lshlrev_b32_e32 v52, 16, v23
	v_and_b32_e32 v53, 0xffff0000, v23
	v_lshlrev_b32_e32 v54, 16, v22
	v_and_b32_e32 v55, 0xffff0000, v22
	v_mov_b32_e32 v72, v66
	v_mov_b32_e32 v73, v70
	v_pk_mul_f32 v[80:81], v[80:81], v[80:81]
	v_and_b32_e32 v65, 0xffff0000, v25
	v_mov_b32_e32 v42, v64
	v_pk_fma_f32 v[72:73], v[72:73], v[72:73], v[80:81]
	v_mov_b32_e32 v84, v55
	v_mov_b32_e32 v82, v54
	v_mov_b32_e32 v80, v53
	v_add_u32_e32 v10, s16, v10
	s_waitcnt vmcnt(1)
	v_pk_add_f32 v[20:21], v[16:17], 1.0 op_sel_hi:[1,0]
	v_lshl_add_u64 v[16:17], s[18:19], 0, v[12:13]
	v_lshl_add_u64 v[16:17], v[16:17], 0, v[162:163]
	v_lshl_add_u64 v[108:109], v[16:17], 0, v[110:111]
	v_or_b32_e32 v162, 0x400, v14
	v_lshl_add_u64 v[36:37], v[44:45], 0, v[162:163]
	v_lshl_add_u64 v[30:31], v[60:61], 0, v[162:163]
	v_or_b32_e32 v162, 0x800, v14
	v_lshl_add_u64 v[40:41], v[44:45], 0, v[162:163]
	v_lshl_add_u64 v[38:39], v[60:61], 0, v[162:163]
	v_or_b32_e32 v162, 0xc00, v14
	v_lshl_add_u64 v[22:23], v[60:61], 0, v[162:163]
	v_lshlrev_b32_e32 v60, 16, v43
	v_and_b32_e32 v61, 0xffff0000, v43
	v_mov_b32_e32 v43, v60
	v_lshl_add_u64 v[24:25], v[44:45], 0, v[162:163]
	v_mov_b32_e32 v44, v65
	v_mov_b32_e32 v45, v61
	v_pk_fma_f32 v[42:43], v[42:43], v[42:43], v[72:73]
	v_pk_add_f32 v[18:19], v[18:19], 1.0 op_sel_hi:[1,0]
	v_pk_fma_f32 v[72:73], v[44:45], v[44:45], v[42:43]
	v_and_b32_e32 v45, 0xffff0000, v46
	v_lshlrev_b32_e32 v44, 16, v46
	v_mov_b32_e32 v85, v45
	v_lshlrev_b32_e32 v42, 16, v47
	v_mov_b32_e32 v83, v44
	v_pk_mul_f32 v[84:85], v[84:85], v[84:85]
	v_and_b32_e32 v43, 0xffff0000, v47
	v_mov_b32_e32 v46, v52
	v_mov_b32_e32 v47, v42
	v_pk_fma_f32 v[82:83], v[82:83], v[82:83], v[84:85]
	v_mov_b32_e32 v81, v43
	v_pk_fma_f32 v[46:47], v[46:47], v[46:47], v[82:83]
	s_add_u32 s18, s18, s24
	v_pk_fma_f32 v[46:47], v[80:81], v[80:81], v[46:47]
	v_mov_b32_e32 v80, v68
	v_mov_b32_e32 v81, v62
	v_mov_b32_e32 v62, v69
	v_pk_add_f32 v[62:63], v[80:81], v[62:63]
	v_mov_b32_e32 v68, v46
	v_mov_b32_e32 v69, v72
	v_pk_add_f32 v[62:63], v[62:63], v[68:69]
	v_mov_b32_e32 v72, v47
	v_pk_add_f32 v[46:47], v[62:63], v[72:73]
	ds_bpermute_b32 v63, v11, v47
	ds_bpermute_b32 v62, v11, v46
	s_addc_u32 s19, s19, s25
	s_add_u32 s14, s14, s24
	s_addc_u32 s15, s15, s25
	s_waitcnt lgkmcnt(0)
	v_pk_add_f32 v[46:47], v[46:47], v[62:63]
	ds_bpermute_b32 v63, v74, v47
	ds_bpermute_b32 v62, v74, v46
	s_waitcnt lgkmcnt(0)
	v_pk_add_f32 v[46:47], v[46:47], v[62:63]
	ds_bpermute_b32 v63, v75, v47
	ds_bpermute_b32 v62, v75, v46
	s_waitcnt lgkmcnt(0)
	v_pk_add_f32 v[46:47], v[46:47], v[62:63]
	ds_bpermute_b32 v63, v76, v47
	ds_bpermute_b32 v62, v76, v46
	s_waitcnt lgkmcnt(0)
	v_pk_add_f32 v[46:47], v[46:47], v[62:63]
	ds_bpermute_b32 v63, v77, v47
	ds_bpermute_b32 v62, v77, v46
	s_waitcnt lgkmcnt(0)
	v_pk_add_f32 v[46:47], v[46:47], v[62:63]
	ds_bpermute_b32 v63, v78, v47
	ds_bpermute_b32 v62, v78, v46
	s_waitcnt lgkmcnt(0)
	v_pk_add_f32 v[46:47], v[46:47], v[62:63]
	s_nop 0
	v_pk_fma_f32 v[62:63], v[46:47], s[30:31], v[164:165] op_sel_hi:[1,0,0]
	s_nop 0
	v_mul_f32_e32 v11, 0x4b800000, v63
	v_cmp_gt_f32_e64 s[38:39], s50, v63
	v_cmp_gt_f32_e32 vcc, s50, v62
	s_nop 0
	v_cndmask_b32_e64 v11, v63, v11, s[38:39]
	v_rsq_f32_e32 v11, v11
	s_nop 0
	v_mul_f32_e32 v15, 0x45800000, v11
	v_cndmask_b32_e64 v68, v11, v15, s[38:39]
	v_mul_f32_e32 v11, 0x4b800000, v62
	v_cndmask_b32_e32 v11, v62, v11, vcc
	v_rsq_f32_e32 v11, v11
	v_pk_mul_f32 v[72:73], v[68:69], v[58:59] op_sel_hi:[0,1]
	v_pk_mul_f32 v[32:33], v[68:69], v[32:33] op_sel_hi:[0,1]
	s_waitcnt vmcnt(0)
	v_pk_mul_f32 v[32:33], v[6:7], v[32:33]
	v_mul_f32_e32 v15, 0x45800000, v11
	v_cndmask_b32_e32 v58, v11, v15, vcc
	v_pk_mul_f32 v[34:35], v[58:59], v[34:35] op_sel_hi:[0,1]
	v_pk_mul_f32 v[6:7], v[6:7], v[34:35]
	v_pk_fma_f32 v[32:33], v[32:33], v[20:21], v[2:3]
	v_pk_mul_f32 v[28:29], v[68:69], v[28:29] op_sel_hi:[0,1]
	v_pk_fma_f32 v[2:3], v[20:21], v[6:7], v[2:3]
	v_pk_mul_f32 v[6:7], v[58:59], v[26:27] op_sel_hi:[0,1]
	v_pk_mul_f32 v[28:29], v[8:9], v[28:29]
	v_pk_mul_f32 v[6:7], v[8:9], v[6:7]
	v_pk_fma_f32 v[28:29], v[28:29], v[18:19], v[4:5]
	v_pk_fma_f32 v[4:5], v[18:19], v[6:7], v[4:5]
	v_cvt_pk_bf16_f32 v32, v32, v33
	v_cvt_pk_bf16_f32 v33, v28, v29
	v_cvt_pk_bf16_f32 v2, v2, v3
	v_cvt_pk_bf16_f32 v3, v4, v5
	v_cndmask_b32_e64 v100, v32, v2, s[78:79]
	v_cndmask_b32_e64 v101, v33, v3, s[78:79]
	s_nop 1
	v_mov_b32_dpp v102, v100 quad_perm:[1,0,3,2] row_mask:0xf bank_mask:0xf
	v_mov_b32_dpp v103, v101 quad_perm:[1,0,3,2] row_mask:0xf bank_mask:0xf
	v_cndmask_b32_e64 v104, v102, v32, s[78:79]
	v_cndmask_b32_e64 v105, v103, v33, s[78:79]
	v_cndmask_b32_e64 v106, v2, v102, s[78:79]
	v_cndmask_b32_e64 v107, v3, v103, s[78:79]
	global_store_dwordx4 v[108:109], v[104:107], off sc1
	global_load_dwordx4 v[2:5], v14, s[6:7] offset:1024
	s_nop 0
	global_load_dwordx4 v[6:9], v[36:37], off
	global_load_dwordx4 v[18:21], v[30:31], off
	v_pk_mul_f32 v[74:75], v[68:69], v[56:57] op_sel_hi:[0,1]
	v_pk_mul_f32 v[26:27], v[58:59], v[50:51] op_sel_hi:[0,1]
	v_pk_mul_f32 v[34:35], v[58:59], v[48:49] op_sel_hi:[0,1]
	v_pk_mul_f32 v[56:57], v[68:69], v[66:67] op_sel_hi:[0,1]
	v_pk_mul_f32 v[46:47], v[68:69], v[64:65] op_sel_hi:[0,1]
	v_pk_mul_f32 v[48:49], v[58:59], v[54:55] op_sel_hi:[0,1]
	v_pk_mul_f32 v[50:51], v[58:59], v[52:53] op_sel_hi:[0,1]
	v_pk_mul_f32 v[32:33], v[68:69], v[70:71] op_sel_hi:[0,1]
	v_pk_mul_f32 v[28:29], v[68:69], v[60:61] op_sel_hi:[0,1]
	v_cmp_lt_i32_e32 vcc, s51, v10
	s_or_b64 s[12:13], vcc, s[12:13]
	s_waitcnt vmcnt(2)
	v_pk_mul_f32 v[30:31], v[72:73], v[2:3]
	v_pk_mul_f32 v[36:37], v[74:75], v[4:5]
	s_waitcnt vmcnt(0)
	v_pk_add_f32 v[18:19], v[18:19], 1.0 op_sel_hi:[1,0]
	v_pk_add_f32 v[20:21], v[20:21], 1.0 op_sel_hi:[1,0]
	v_pk_mul_f32 v[2:3], v[2:3], v[26:27]
	v_pk_mul_f32 v[4:5], v[4:5], v[34:35]
	v_pk_fma_f32 v[30:31], v[30:31], v[18:19], v[6:7]
	v_pk_fma_f32 v[36:37], v[36:37], v[20:21], v[8:9]
	v_pk_fma_f32 v[2:3], v[18:19], v[2:3], v[6:7]
	v_pk_fma_f32 v[4:5], v[20:21], v[4:5], v[8:9]
	v_cvt_pk_bf16_f32 v30, v30, v31
	v_cvt_pk_bf16_f32 v31, v36, v37
	v_cvt_pk_bf16_f32 v2, v2, v3
	v_cvt_pk_bf16_f32 v3, v4, v5
	v_cndmask_b32_e64 v100, v30, v2, s[78:79]
	v_cndmask_b32_e64 v101, v31, v3, s[78:79]
	s_nop 1
	v_mov_b32_dpp v102, v100 quad_perm:[1,0,3,2] row_mask:0xf bank_mask:0xf
	v_mov_b32_dpp v103, v101 quad_perm:[1,0,3,2] row_mask:0xf bank_mask:0xf
	v_cndmask_b32_e64 v104, v102, v30, s[78:79]
	v_cndmask_b32_e64 v105, v103, v31, s[78:79]
	v_cndmask_b32_e64 v106, v2, v102, s[78:79]
	v_cndmask_b32_e64 v107, v3, v103, s[78:79]
	global_store_dwordx4 v[108:109], v[104:107], off offset:512 sc1
	global_load_dwordx4 v[2:5], v14, s[6:7] offset:2048
	s_nop 0
	global_load_dwordx4 v[6:9], v[40:41], off
	global_load_dwordx4 v[18:21], v[38:39], off
	s_waitcnt vmcnt(2)
	v_pk_mul_f32 v[26:27], v[56:57], v[2:3]
	v_pk_mul_f32 v[30:31], v[46:47], v[4:5]
	s_waitcnt vmcnt(0)
	v_pk_add_f32 v[18:19], v[18:19], 1.0 op_sel_hi:[1,0]
	v_pk_add_f32 v[20:21], v[20:21], 1.0 op_sel_hi:[1,0]
	v_pk_mul_f32 v[2:3], v[48:49], v[2:3]
	v_pk_mul_f32 v[4:5], v[50:51], v[4:5]
	v_pk_fma_f32 v[26:27], v[26:27], v[18:19], v[6:7]
	v_pk_fma_f32 v[30:31], v[30:31], v[20:21], v[8:9]
	v_pk_fma_f32 v[2:3], v[2:3], v[18:19], v[6:7]
	v_pk_fma_f32 v[4:5], v[4:5], v[20:21], v[8:9]
	v_cvt_pk_bf16_f32 v26, v26, v27
	v_cvt_pk_bf16_f32 v27, v30, v31
	v_cvt_pk_bf16_f32 v2, v2, v3
	v_cvt_pk_bf16_f32 v3, v4, v5
	v_cndmask_b32_e64 v100, v26, v2, s[78:79]
	v_cndmask_b32_e64 v101, v27, v3, s[78:79]
	s_nop 1
	v_mov_b32_dpp v102, v100 quad_perm:[1,0,3,2] row_mask:0xf bank_mask:0xf
	v_mov_b32_dpp v103, v101 quad_perm:[1,0,3,2] row_mask:0xf bank_mask:0xf
	v_cndmask_b32_e64 v104, v102, v26, s[78:79]
	v_cndmask_b32_e64 v105, v103, v27, s[78:79]
	v_cndmask_b32_e64 v106, v2, v102, s[78:79]
	v_cndmask_b32_e64 v107, v3, v103, s[78:79]
	global_store_dwordx4 v[108:109], v[104:107], off offset:1024 sc1
	global_load_dwordx4 v[2:5], v14, s[6:7] offset:3072
	s_nop 0
	global_load_dwordx4 v[6:9], v[24:25], off
	global_load_dwordx4 v[18:21], v[22:23], off
	s_waitcnt vmcnt(2)
	v_pk_mul_f32 v[14:15], v[32:33], v[2:3]
	v_pk_mul_f32 v[22:23], v[28:29], v[4:5]
	s_waitcnt vmcnt(0)
	v_pk_add_f32 v[18:19], v[18:19], 1.0 op_sel_hi:[1,0]
	v_pk_add_f32 v[20:21], v[20:21], 1.0 op_sel_hi:[1,0]
	v_pk_fma_f32 v[14:15], v[14:15], v[18:19], v[6:7]
	v_pk_fma_f32 v[22:23], v[22:23], v[20:21], v[8:9]
	v_cvt_pk_bf16_f32 v14, v14, v15
	v_cvt_pk_bf16_f32 v15, v22, v23
	v_mov_b32_e32 v112, v14
	v_mov_b32_e32 v113, v15
	v_pk_mul_f32 v[14:15], v[58:59], v[44:45] op_sel_hi:[0,1]
	v_pk_mul_f32 v[2:3], v[14:15], v[2:3]
	s_nop 0
	v_pk_fma_f32 v[2:3], v[2:3], v[18:19], v[6:7]
	v_pk_mul_f32 v[6:7], v[58:59], v[42:43] op_sel_hi:[0,1]
	v_pk_mul_f32 v[4:5], v[6:7], v[4:5]
	v_cvt_pk_bf16_f32 v2, v2, v3
	v_pk_fma_f32 v[4:5], v[4:5], v[20:21], v[8:9]
	s_nop 0
	v_cvt_pk_bf16_f32 v3, v4, v5
	v_cndmask_b32_e64 v100, v112, v2, s[78:79]
	v_cndmask_b32_e64 v101, v113, v3, s[78:79]
	s_nop 1
	v_mov_b32_dpp v102, v100 quad_perm:[1,0,3,2] row_mask:0xf bank_mask:0xf
	v_mov_b32_dpp v103, v101 quad_perm:[1,0,3,2] row_mask:0xf bank_mask:0xf
	v_cndmask_b32_e64 v104, v102, v112, s[78:79]
	v_cndmask_b32_e64 v105, v103, v113, s[78:79]
	v_cndmask_b32_e64 v106, v2, v102, s[78:79]
	v_cndmask_b32_e64 v107, v3, v103, s[78:79]
	global_store_dwordx4 v[108:109], v[104:107], off offset:1536 sc1
	s_andn2_b64 exec, exec, s[12:13]
	s_cbranch_execnz .LBB0_205
